# previous + in-proj GEMM K-loop LDS-DMA in SGPR-base form (12 of 16 64-bit VALU address adds per 2 K-tiles removed)
# baseline (speedup 1.0000x reference)
.LBB0_168:
	s_add_u32 s46, vcc_lo, 0xfffc0080
	s_addc_u32 s47, vcc_hi, -1
	s_add_i32 s85, 0, 0x10000
	s_cmp_eq_u32 s84, 12
	s_cselect_b32 s49, s17, s47
	s_cselect_b32 s48, s22, s46
	v_add_u32_e32 v0, s85, v220
	s_cselect_b32 s47, s43, s81
	s_cselect_b32 s46, s51, s63
	s_add_i32 s90, 0, 0x14000
	ds_read_b128 v[130:133], v0
	ds_read_b128 v[134:137], v0 offset:1024
	ds_read_b128 v[138:141], v0 offset:2048
	ds_read_b128 v[142:145], v0 offset:3072
	v_add_u32_e32 v0, s90, v220
	ds_read_b128 v[146:149], v0
	ds_read_b128 v[150:153], v0 offset:1024
	ds_read_b128 v[154:157], v0 offset:2048
	ds_read_b128 v[170:173], v0 offset:3072
	s_add_i32 m0, s74, 0xc000
	ds_read_b128 v[174:177], v224
	ds_read_b128 v[186:189], v224 offset:1024
	ds_read_b128 v[190:193], v224 offset:2048
	ds_read_b128 v[194:197], v224 offset:3072
	ds_read_b128 v[198:201], v224 offset:4096
	ds_read_b128 v[202:205], v224 offset:5120
	ds_read_b128 v[206:209], v224 offset:6144
	ds_read_b128 v[226:229], v224 offset:7168
	global_load_lds_dwordx4 v166, vcc
	s_add_i32 m0, s74, 0xe000
	s_nop 0
	global_load_lds_dwordx4 v168, vcc
	s_waitcnt vmcnt(8)
	s_waitcnt lgkmcnt(0)
	s_barrier
	s_setprio 1
	s_waitcnt lgkmcnt(0)
	v_mfma_f32_16x16x32_bf16 v[126:129], v[130:133], v[174:177], v[126:129]
	v_mfma_f32_16x16x32_bf16 v[122:125], v[138:141], v[174:177], v[122:125]
	v_mfma_f32_16x16x32_bf16 v[114:117], v[130:133], v[190:193], v[114:117]
	v_mfma_f32_16x16x32_bf16 v[106:109], v[138:141], v[190:193], v[106:109]
	v_mfma_f32_16x16x32_bf16 v[98:101], v[130:133], v[198:201], v[98:101]
	v_mfma_f32_16x16x32_bf16 v[90:93], v[138:141], v[198:201], v[90:93]
	v_mfma_f32_16x16x32_bf16 v[82:85], v[130:133], v[206:209], v[82:85]
	v_mfma_f32_16x16x32_bf16 v[74:77], v[138:141], v[206:209], v[74:77]
	v_mfma_f32_16x16x32_bf16 v[126:129], v[134:137], v[186:189], v[126:129]
	v_mfma_f32_16x16x32_bf16 v[122:125], v[142:145], v[186:189], v[122:125]
	v_mfma_f32_16x16x32_bf16 v[114:117], v[134:137], v[194:197], v[114:117]
	v_mfma_f32_16x16x32_bf16 v[106:109], v[142:145], v[194:197], v[106:109]
	v_mfma_f32_16x16x32_bf16 v[98:101], v[134:137], v[202:205], v[98:101]
	v_mfma_f32_16x16x32_bf16 v[90:93], v[142:145], v[202:205], v[90:93]
	v_mfma_f32_16x16x32_bf16 v[82:85], v[134:137], v[226:229], v[82:85]
	v_mfma_f32_16x16x32_bf16 v[74:77], v[142:145], v[226:229], v[74:77]
	s_setprio 0
	s_setprio 1
	v_mfma_f32_16x16x32_bf16 v[118:121], v[146:149], v[174:177], v[118:121]
	v_mfma_f32_16x16x32_bf16 v[110:113], v[154:157], v[174:177], v[110:113]
	v_mfma_f32_16x16x32_bf16 v[102:105], v[146:149], v[190:193], v[102:105]
	v_mfma_f32_16x16x32_bf16 v[94:97], v[154:157], v[190:193], v[94:97]
	v_mfma_f32_16x16x32_bf16 v[86:89], v[146:149], v[198:201], v[86:89]
	v_mfma_f32_16x16x32_bf16 v[78:81], v[154:157], v[198:201], v[78:81]
	v_mfma_f32_16x16x32_bf16 v[70:73], v[146:149], v[206:209], v[70:73]
	v_mfma_f32_16x16x32_bf16 v[66:69], v[154:157], v[206:209], v[66:69]
	v_mfma_f32_16x16x32_bf16 v[118:121], v[150:153], v[186:189], v[118:121]
	v_mfma_f32_16x16x32_bf16 v[110:113], v[170:173], v[186:189], v[110:113]
	v_mfma_f32_16x16x32_bf16 v[102:105], v[150:153], v[194:197], v[102:105]
	v_mfma_f32_16x16x32_bf16 v[94:97], v[170:173], v[194:197], v[94:97]
	v_mfma_f32_16x16x32_bf16 v[86:89], v[150:153], v[202:205], v[86:89]
	v_mfma_f32_16x16x32_bf16 v[78:81], v[170:173], v[202:205], v[78:81]
	v_mfma_f32_16x16x32_bf16 v[70:73], v[150:153], v[226:229], v[70:73]
	v_mfma_f32_16x16x32_bf16 v[66:69], v[170:173], v[226:229], v[66:69]
	s_setprio 0
	s_barrier
	s_add_i32 s85, s85, s31
	s_mov_b32 m0, s85
	ds_read_b128 v[174:177], v224 offset:16384
	ds_read_b128 v[186:189], v224 offset:17408
	ds_read_b128 v[190:193], v224 offset:18432
	ds_read_b128 v[194:197], v224 offset:19456
	ds_read_b128 v[198:201], v224 offset:20480
	ds_read_b128 v[202:205], v224 offset:21504
	ds_read_b128 v[206:209], v224 offset:22528
	ds_read_b128 v[226:229], v224 offset:23552
	global_load_lds_dwordx4 v160, s[46:47]
	s_add_i32 m0, s85, 0x2000
	s_add_u32 s88, s46, 0x40000
	s_addc_u32 s89, s47, 0
	s_add_i32 s85, s90, s31
	global_load_lds_dwordx4 v164, s[46:47]
	s_mov_b32 m0, s85
	v_lshl_add_u64 v[234:235], s[48:49], 0, v[162:163]
	global_load_lds_dwordx4 v160, s[88:89]
	s_add_i32 m0, s85, 0x2000
	s_nop 0
	global_load_lds_dwordx4 v164, s[88:89]
	v_lshl_add_u64 v[232:233], s[48:49], 0, v[158:159]
	s_mov_b32 m0, s74
	s_nop 0
	global_load_lds_dwordx4 v[232:233], off
	s_mov_b32 m0, s75
	s_nop 0
	global_load_lds_dwordx4 v[234:235], off
	s_waitcnt vmcnt(8)
	s_waitcnt lgkmcnt(0)
	s_barrier
	s_setprio 1
	s_waitcnt lgkmcnt(0)
	v_mfma_f32_16x16x32_bf16 v[62:65], v[130:133], v[174:177], v[62:65]
	v_mfma_f32_16x16x32_bf16 v[58:61], v[138:141], v[174:177], v[58:61]
	v_mfma_f32_16x16x32_bf16 v[50:53], v[130:133], v[190:193], v[50:53]
	v_mfma_f32_16x16x32_bf16 v[42:45], v[138:141], v[190:193], v[42:45]
	v_mfma_f32_16x16x32_bf16 v[34:37], v[130:133], v[198:201], v[34:37]
	v_mfma_f32_16x16x32_bf16 v[26:29], v[138:141], v[198:201], v[26:29]
	v_mfma_f32_16x16x32_bf16 v[18:21], v[130:133], v[206:209], v[18:21]
	v_mfma_f32_16x16x32_bf16 v[10:13], v[138:141], v[206:209], v[10:13]
	v_mfma_f32_16x16x32_bf16 v[62:65], v[134:137], v[186:189], v[62:65]
	v_mfma_f32_16x16x32_bf16 v[58:61], v[142:145], v[186:189], v[58:61]
	v_mfma_f32_16x16x32_bf16 v[50:53], v[134:137], v[194:197], v[50:53]
	v_mfma_f32_16x16x32_bf16 v[42:45], v[142:145], v[194:197], v[42:45]
	v_mfma_f32_16x16x32_bf16 v[34:37], v[134:137], v[202:205], v[34:37]
	v_mfma_f32_16x16x32_bf16 v[26:29], v[142:145], v[202:205], v[26:29]
	v_mfma_f32_16x16x32_bf16 v[18:21], v[134:137], v[226:229], v[18:21]
	v_mfma_f32_16x16x32_bf16 v[10:13], v[142:145], v[226:229], v[10:13]
	s_setprio 0
	s_setprio 1
	v_mfma_f32_16x16x32_bf16 v[54:57], v[146:149], v[174:177], v[54:57]
	v_mfma_f32_16x16x32_bf16 v[46:49], v[154:157], v[174:177], v[46:49]
	v_mfma_f32_16x16x32_bf16 v[38:41], v[146:149], v[190:193], v[38:41]
	v_mfma_f32_16x16x32_bf16 v[30:33], v[154:157], v[190:193], v[30:33]
	v_mfma_f32_16x16x32_bf16 v[22:25], v[146:149], v[198:201], v[22:25]
	v_mfma_f32_16x16x32_bf16 v[14:17], v[154:157], v[198:201], v[14:17]
	v_mfma_f32_16x16x32_bf16 v[6:9], v[146:149], v[206:209], v[6:9]
	v_mfma_f32_16x16x32_bf16 v[2:5], v[154:157], v[206:209], v[2:5]
	v_mfma_f32_16x16x32_bf16 v[54:57], v[150:153], v[186:189], v[54:57]
	v_mfma_f32_16x16x32_bf16 v[46:49], v[170:173], v[186:189], v[46:49]
	v_mfma_f32_16x16x32_bf16 v[38:41], v[150:153], v[194:197], v[38:41]
	v_mfma_f32_16x16x32_bf16 v[30:33], v[170:173], v[194:197], v[30:33]
	v_mfma_f32_16x16x32_bf16 v[22:25], v[150:153], v[202:205], v[22:25]
	v_mfma_f32_16x16x32_bf16 v[14:17], v[170:173], v[202:205], v[14:17]
	v_mfma_f32_16x16x32_bf16 v[6:9], v[150:153], v[226:229], v[6:9]
	v_mfma_f32_16x16x32_bf16 v[2:5], v[170:173], v[226:229], v[2:5]
	s_setprio 0
	s_barrier
	s_add_i32 s85, 0, 0x18000
	v_add_u32_e32 v0, s85, v220
	s_add_i32 s88, 0, 0x1c000
	ds_read_b128 v[130:133], v0
	ds_read_b128 v[134:137], v0 offset:1024
	ds_read_b128 v[138:141], v0 offset:2048
	ds_read_b128 v[142:145], v0 offset:3072
	v_add_u32_e32 v0, s88, v220
	ds_read_b128 v[146:149], v0
	ds_read_b128 v[150:153], v0 offset:1024
	ds_read_b128 v[154:157], v0 offset:2048
	ds_read_b128 v[170:173], v0 offset:3072
	s_add_u32 s48, s48, 0x40000
	s_addc_u32 s49, s49, 0
	s_mov_b32 m0, s76
	ds_read_b128 v[174:177], v224 offset:32768
	ds_read_b128 v[186:189], v224 offset:33792
	ds_read_b128 v[190:193], v224 offset:34816
	ds_read_b128 v[194:197], v224 offset:35840
	ds_read_b128 v[198:201], v224 offset:36864
	ds_read_b128 v[202:205], v224 offset:37888
	ds_read_b128 v[206:209], v224 offset:38912
	ds_read_b128 v[226:229], v224 offset:39936
	global_load_lds_dwordx4 v158, s[48:49]
	s_mov_b32 m0, s77
	s_nop 0
	global_load_lds_dwordx4 v162, s[48:49]
	s_waitcnt vmcnt(8)
	s_waitcnt lgkmcnt(0)
	s_barrier
	s_setprio 1
	s_waitcnt lgkmcnt(0)
	v_mfma_f32_16x16x32_bf16 v[126:129], v[130:133], v[174:177], v[126:129]
	v_mfma_f32_16x16x32_bf16 v[122:125], v[138:141], v[174:177], v[122:125]
	v_mfma_f32_16x16x32_bf16 v[114:117], v[130:133], v[190:193], v[114:117]
	v_mfma_f32_16x16x32_bf16 v[106:109], v[138:141], v[190:193], v[106:109]
	v_mfma_f32_16x16x32_bf16 v[98:101], v[130:133], v[198:201], v[98:101]
	v_mfma_f32_16x16x32_bf16 v[90:93], v[138:141], v[198:201], v[90:93]
	v_mfma_f32_16x16x32_bf16 v[82:85], v[130:133], v[206:209], v[82:85]
	v_mfma_f32_16x16x32_bf16 v[74:77], v[138:141], v[206:209], v[74:77]
	v_mfma_f32_16x16x32_bf16 v[126:129], v[134:137], v[186:189], v[126:129]
	v_mfma_f32_16x16x32_bf16 v[122:125], v[142:145], v[186:189], v[122:125]
	v_mfma_f32_16x16x32_bf16 v[114:117], v[134:137], v[194:197], v[114:117]
	v_mfma_f32_16x16x32_bf16 v[106:109], v[142:145], v[194:197], v[106:109]
	v_mfma_f32_16x16x32_bf16 v[98:101], v[134:137], v[202:205], v[98:101]
	v_mfma_f32_16x16x32_bf16 v[90:93], v[142:145], v[202:205], v[90:93]
	v_mfma_f32_16x16x32_bf16 v[82:85], v[134:137], v[226:229], v[82:85]
	v_mfma_f32_16x16x32_bf16 v[74:77], v[142:145], v[226:229], v[74:77]
	s_setprio 0
	s_setprio 1
	v_mfma_f32_16x16x32_bf16 v[118:121], v[146:149], v[174:177], v[118:121]
	v_mfma_f32_16x16x32_bf16 v[110:113], v[154:157], v[174:177], v[110:113]
	v_mfma_f32_16x16x32_bf16 v[102:105], v[146:149], v[190:193], v[102:105]
	v_mfma_f32_16x16x32_bf16 v[94:97], v[154:157], v[190:193], v[94:97]
	v_mfma_f32_16x16x32_bf16 v[86:89], v[146:149], v[198:201], v[86:89]
	v_mfma_f32_16x16x32_bf16 v[78:81], v[154:157], v[198:201], v[78:81]
	v_mfma_f32_16x16x32_bf16 v[70:73], v[146:149], v[206:209], v[70:73]
	v_mfma_f32_16x16x32_bf16 v[66:69], v[154:157], v[206:209], v[66:69]
	v_mfma_f32_16x16x32_bf16 v[118:121], v[150:153], v[186:189], v[118:121]
	v_mfma_f32_16x16x32_bf16 v[110:113], v[170:173], v[186:189], v[110:113]
	v_mfma_f32_16x16x32_bf16 v[102:105], v[150:153], v[194:197], v[102:105]
	v_mfma_f32_16x16x32_bf16 v[94:97], v[170:173], v[194:197], v[94:97]
	v_mfma_f32_16x16x32_bf16 v[86:89], v[150:153], v[202:205], v[86:89]
	v_mfma_f32_16x16x32_bf16 v[78:81], v[170:173], v[202:205], v[78:81]
	v_mfma_f32_16x16x32_bf16 v[70:73], v[150:153], v[226:229], v[70:73]
	v_mfma_f32_16x16x32_bf16 v[66:69], v[170:173], v[226:229], v[66:69]
	s_setprio 0
	s_barrier
	s_add_i32 s48, s85, s31
	s_add_u32 s100, s46, 0x80
	s_addc_u32 s101, s47, 0
	s_mov_b32 m0, s48
	ds_read_b128 v[174:177], v224 offset:49152
	ds_read_b128 v[186:189], v224 offset:50176
	ds_read_b128 v[190:193], v224 offset:51200
	ds_read_b128 v[194:197], v224 offset:52224
	ds_read_b128 v[198:201], v224 offset:53248
	ds_read_b128 v[202:205], v224 offset:54272
	ds_read_b128 v[206:209], v224 offset:55296
	ds_read_b128 v[226:229], v224 offset:56320
	global_load_lds_dwordx4 v160, s[100:101]
	s_add_i32 m0, s48, 0x2000
	s_add_u32 s46, s46, 0x40080
	s_addc_u32 s47, s47, 0
	s_add_i32 s48, s88, s31
	global_load_lds_dwordx4 v164, s[100:101]
	s_mov_b32 m0, s48
	s_nop 0
	global_load_lds_dwordx4 v160, s[46:47]
	s_add_i32 m0, s48, 0x2000
	s_nop 0
	global_load_lds_dwordx4 v164, s[46:47]
	v_lshl_add_u64 v[212:213], v[232:233], 0, s[10:11]
	s_mov_b32 m0, s78
	s_nop 0
	global_load_lds_dwordx4 v[212:213], off
	v_lshl_add_u64 v[212:213], v[234:235], 0, s[10:11]
	s_mov_b32 m0, s79
	s_nop 0
	global_load_lds_dwordx4 v[212:213], off
	s_waitcnt vmcnt(8)
	s_waitcnt lgkmcnt(0)
	s_barrier
	s_setprio 1
	s_waitcnt lgkmcnt(0)
	v_mfma_f32_16x16x32_bf16 v[62:65], v[130:133], v[174:177], v[62:65]
	v_mfma_f32_16x16x32_bf16 v[58:61], v[138:141], v[174:177], v[58:61]
	v_mfma_f32_16x16x32_bf16 v[50:53], v[130:133], v[190:193], v[50:53]
	v_mfma_f32_16x16x32_bf16 v[42:45], v[138:141], v[190:193], v[42:45]
	v_mfma_f32_16x16x32_bf16 v[34:37], v[130:133], v[198:201], v[34:37]
	v_mfma_f32_16x16x32_bf16 v[26:29], v[138:141], v[198:201], v[26:29]
	v_mfma_f32_16x16x32_bf16 v[18:21], v[130:133], v[206:209], v[18:21]
	v_mfma_f32_16x16x32_bf16 v[10:13], v[138:141], v[206:209], v[10:13]
	v_mfma_f32_16x16x32_bf16 v[62:65], v[134:137], v[186:189], v[62:65]
	v_mfma_f32_16x16x32_bf16 v[58:61], v[142:145], v[186:189], v[58:61]
	v_mfma_f32_16x16x32_bf16 v[50:53], v[134:137], v[194:197], v[50:53]
	v_mfma_f32_16x16x32_bf16 v[42:45], v[142:145], v[194:197], v[42:45]
	v_mfma_f32_16x16x32_bf16 v[34:37], v[134:137], v[202:205], v[34:37]
	v_mfma_f32_16x16x32_bf16 v[26:29], v[142:145], v[202:205], v[26:29]
	v_mfma_f32_16x16x32_bf16 v[18:21], v[134:137], v[226:229], v[18:21]
	v_mfma_f32_16x16x32_bf16 v[10:13], v[142:145], v[226:229], v[10:13]
	s_setprio 0
	s_setprio 1
	v_mfma_f32_16x16x32_bf16 v[54:57], v[146:149], v[174:177], v[54:57]
	v_mfma_f32_16x16x32_bf16 v[46:49], v[154:157], v[174:177], v[46:49]
	v_mfma_f32_16x16x32_bf16 v[38:41], v[146:149], v[190:193], v[38:41]
	v_mfma_f32_16x16x32_bf16 v[30:33], v[154:157], v[190:193], v[30:33]
	v_mfma_f32_16x16x32_bf16 v[22:25], v[146:149], v[198:201], v[22:25]
	v_mfma_f32_16x16x32_bf16 v[14:17], v[154:157], v[198:201], v[14:17]
	v_mfma_f32_16x16x32_bf16 v[6:9], v[146:149], v[206:209], v[6:9]
	v_mfma_f32_16x16x32_bf16 v[2:5], v[154:157], v[206:209], v[2:5]
	v_mfma_f32_16x16x32_bf16 v[54:57], v[150:153], v[186:189], v[54:57]
	v_mfma_f32_16x16x32_bf16 v[46:49], v[170:173], v[186:189], v[46:49]
	v_mfma_f32_16x16x32_bf16 v[38:41], v[150:153], v[194:197], v[38:41]
	v_mfma_f32_16x16x32_bf16 v[30:33], v[170:173], v[194:197], v[30:33]
	v_mfma_f32_16x16x32_bf16 v[22:25], v[150:153], v[202:205], v[22:25]
	v_mfma_f32_16x16x32_bf16 v[14:17], v[170:173], v[202:205], v[14:17]
	v_mfma_f32_16x16x32_bf16 v[6:9], v[150:153], v[226:229], v[6:9]
	v_mfma_f32_16x16x32_bf16 v[2:5], v[170:173], v[226:229], v[2:5]
	s_setprio 0
	s_barrier
	s_add_i32 s84, s84, 2
	s_add_u32 vcc_lo, vcc_lo, 0x100
	s_addc_u32 vcc_hi, vcc_hi, 0
	s_add_u32 s63, s63, 0x100
	s_addc_u32 s81, s81, 0
	s_cmp_gt_u32 s84, 13
	s_cbranch_scc0 .LBB0_168
	s_and_b64 vcc, exec, s[94:95]
	s_cbranch_vccnz .LBB0_173
	s_mov_b64 s[46:47], -1
	s_and_b64 vcc, exec, s[70:71]
	v_lshl_add_u32 v170, s8, 8, v219
	s_cbranch_vccnz .LBB0_174

.LBB0_280:
	s_waitcnt lgkmcnt(5)
	v_mfma_f32_32x32x16_bf16 v[66:81], v[166:169], v[134:137], v[66:81]
	v_add_f32_e32 v174, v114, v115
	v_add_f32_e32 v175, v116, v117
	v_add_f32_e32 v176, v118, v119
	v_add_f32_e32 v177, v120, v121
	v_add_f32_e32 v174, v174, v122
	s_waitcnt lgkmcnt(4)
	v_mfma_f32_32x32x16_bf16 v[82:97], v[162:165], v[134:137], v[82:97]
	v_add_f32_e32 v175, v175, v123
	v_add_f32_e32 v176, v176, v124
	v_add_f32_e32 v177, v177, v125
	v_add_f32_e32 v174, v174, v126
	v_add_f32_e32 v175, v175, v127
	s_waitcnt lgkmcnt(3)
	v_mfma_f32_32x32x16_bf16 v[66:81], v[158:161], v[138:141], v[66:81]
	v_add_f32_e32 v176, v176, v128
	v_add_f32_e32 v177, v177, v129
	v_add_f32_e32 v174, v174, v98
	v_add_f32_e32 v175, v175, v99
	v_add_f32_e32 v176, v176, v100
	s_waitcnt lgkmcnt(2)
	v_mfma_f32_32x32x16_bf16 v[82:97], v[154:157], v[138:141], v[82:97]
	v_add_f32_e32 v177, v177, v101
	v_add_f32_e32 v174, v174, v102
	v_add_f32_e32 v175, v175, v103
	v_add_f32_e32 v176, v176, v104
	v_add_f32_e32 v177, v177, v105
	s_waitcnt lgkmcnt(1)
	v_mfma_f32_32x32x16_bf16 v[66:81], v[150:153], v[142:145], v[66:81]
	v_add_f32_e32 v174, v174, v106
	v_add_f32_e32 v175, v175, v107
	v_add_f32_e32 v176, v176, v108
	v_add_f32_e32 v177, v177, v109
	s_waitcnt lgkmcnt(0)
	v_mfma_f32_32x32x16_bf16 v[82:97], v[146:149], v[142:145], v[82:97]
	v_add_f32_e32 v174, v174, v110
	v_add_f32_e32 v175, v175, v111
	v_add_f32_e32 v176, v176, v112
	v_add_f32_e32 v177, v177, v113
	v_add_f32_e32 v174, v174, v175
	v_add_f32_e32 v176, v176, v177
	v_cvt_pk_bf16_f32 v113, v112, v113
	v_cvt_pk_bf16_f32 v112, v110, v111
	v_cvt_pk_bf16_f32 v111, v108, v109
	v_cvt_pk_bf16_f32 v110, v106, v107
	v_add_f32_e32 v174, v174, v176
	v_cvt_pk_bf16_f32 v109, v104, v105
	v_cvt_pk_bf16_f32 v108, v102, v103
	v_cvt_pk_bf16_f32 v107, v100, v101
	v_cvt_pk_bf16_f32 v106, v98, v99
	v_cvt_pk_bf16_f32 v98, v114, v115
	v_cvt_pk_bf16_f32 v99, v116, v117
	v_cvt_pk_bf16_f32 v100, v118, v119
	v_cvt_pk_bf16_f32 v101, v120, v121
	v_cvt_pk_bf16_f32 v102, v122, v123
	v_cvt_pk_bf16_f32 v103, v124, v125
	v_cvt_pk_bf16_f32 v104, v126, v127
	v_cvt_pk_bf16_f32 v105, v128, v129
	v_add_f32_e32 v213, v174, v0
	ds_read_b128 v[114:117], v208 offset:49152
	ds_read_b128 v[118:121], v208 offset:53248
	ds_read_b128 v[122:125], v208 offset:57344
	ds_read_b128 v[126:129], v208 offset:61440
	ds_read_b128 v[150:153], v209 offset:53248
	ds_read_b128 v[146:149], v209 offset:49152
	ds_read_b128 v[154:157], v209 offset:57344
	ds_read_b128 v[158:161], v209 offset:61440
	s_and_b32 s0, s77, 0x3f0000
	s_lshl_b32 s22, s0, 1
	s_mov_b32 m0, s73
	s_add_u32 s100, s46, s22
	s_addc_u32 s101, s47, 0
	global_load_lds_dwordx4 v188, s[100:101]
	s_nop 0
	s_mov_b32 m0, s31
	s_lshl_b32 s22, s15, 1
	global_load_lds_dwordx4 v192, s[100:101]
	s_add_u32 s100, s50, s22
	s_addc_u32 s101, s51, 0
	s_mov_b32 m0, s71
	s_nop 0
	global_load_lds_dwordx4 v190, s[100:101]
	s_nop 0
	s_mov_b32 m0, s72
	s_nop 0
	global_load_lds_dwordx4 v194, s[100:101]
	s_waitcnt lgkmcnt(0)
	v_mfma_f32_32x32x16_bf16 v[50:65], v[98:101], v[114:117], v[50:65]
	ds_read_b128 v[114:117], v210 offset:53248
	v_exp_f32_e32 v66, v66
	v_exp_f32_e32 v67, v67
	v_mfma_f32_32x32x16_bf16 v[34:49], v[98:101], v[118:121], v[34:49]
	ds_read_b128 v[118:121], v210 offset:57344
	v_exp_f32_e32 v68, v68
	v_exp_f32_e32 v69, v69
	v_mfma_f32_32x32x16_bf16 v[18:33], v[98:101], v[122:125], v[18:33]
	ds_read_b128 v[122:125], v210 offset:61440
	v_exp_f32_e32 v70, v70
	v_exp_f32_e32 v71, v71
	v_mfma_f32_32x32x16_bf16 v[2:17], v[98:101], v[126:129], v[2:17]
	ds_read_b128 v[98:101], v210 offset:49152
	v_exp_f32_e32 v72, v72
	v_exp_f32_e32 v73, v73
	v_mfma_f32_32x32x16_bf16 v[50:65], v[102:105], v[146:149], v[50:65]
	ds_read_b128 v[126:129], v212 offset:53248
	v_exp_f32_e32 v74, v74
	v_exp_f32_e32 v75, v75
	v_mfma_f32_32x32x16_bf16 v[34:49], v[102:105], v[150:153], v[34:49]
	ds_read_b128 v[146:149], v212 offset:57344
	v_exp_f32_e32 v76, v76
	v_exp_f32_e32 v77, v77
	v_mfma_f32_32x32x16_bf16 v[18:33], v[102:105], v[154:157], v[18:33]
	ds_read_b128 v[150:153], v212 offset:61440
	v_exp_f32_e32 v78, v78
	v_exp_f32_e32 v79, v79
	v_mfma_f32_32x32x16_bf16 v[2:17], v[102:105], v[158:161], v[2:17]
	ds_read_b128 v[102:105], v212 offset:49152
	v_exp_f32_e32 v80, v80
	v_exp_f32_e32 v81, v81
	s_waitcnt lgkmcnt(0)
	v_mfma_f32_32x32x16_bf16 v[50:65], v[106:109], v[98:101], v[50:65]
	v_exp_f32_e32 v82, v82
	v_exp_f32_e32 v83, v83
	v_mfma_f32_32x32x16_bf16 v[34:49], v[106:109], v[114:117], v[34:49]
	v_exp_f32_e32 v84, v84
	v_exp_f32_e32 v85, v85
	v_mfma_f32_32x32x16_bf16 v[18:33], v[106:109], v[118:121], v[18:33]
	v_exp_f32_e32 v86, v86
	v_exp_f32_e32 v87, v87
	v_mfma_f32_32x32x16_bf16 v[2:17], v[106:109], v[122:125], v[2:17]
	v_exp_f32_e32 v88, v88
	v_exp_f32_e32 v89, v89
	v_mfma_f32_32x32x16_bf16 v[50:65], v[110:113], v[102:105], v[50:65]
	v_exp_f32_e32 v90, v90
	v_exp_f32_e32 v91, v91
	v_mfma_f32_32x32x16_bf16 v[34:49], v[110:113], v[126:129], v[34:49]
	v_exp_f32_e32 v92, v92
	v_exp_f32_e32 v93, v93
	v_mfma_f32_32x32x16_bf16 v[18:33], v[110:113], v[146:149], v[18:33]
	v_exp_f32_e32 v94, v94
	v_exp_f32_e32 v95, v95
	v_mfma_f32_32x32x16_bf16 v[2:17], v[110:113], v[150:153], v[2:17]
	v_exp_f32_e32 v96, v96
	v_exp_f32_e32 v97, v97
	s_waitcnt vmcnt(0)
	s_add_i32 s76, s76, 2
	s_add_i32 s77, s77, 0x20000
	s_cmp_gt_u32 s76, 61
	s_waitcnt vmcnt(0)
	s_barrier
	s_cbranch_scc1 .LBB0_295

.LBB0_288:
	s_waitcnt lgkmcnt(5)
	v_mfma_f32_32x32x16_bf16 v[114:129], v[166:169], v[134:137], v[114:129]
	v_add_f32_e32 v174, v66, v67
	v_add_f32_e32 v175, v68, v69
	v_add_f32_e32 v176, v70, v71
	v_add_f32_e32 v177, v72, v73
	v_add_f32_e32 v174, v174, v74
	s_waitcnt lgkmcnt(4)
	v_mfma_f32_32x32x16_bf16 v[98:113], v[162:165], v[134:137], v[98:113]
	v_add_f32_e32 v175, v175, v75
	v_add_f32_e32 v176, v176, v76
	v_add_f32_e32 v177, v177, v77
	v_add_f32_e32 v174, v174, v78
	v_add_f32_e32 v175, v175, v79
	s_waitcnt lgkmcnt(3)
	v_mfma_f32_32x32x16_bf16 v[114:129], v[158:161], v[138:141], v[114:129]
	v_add_f32_e32 v176, v176, v80
	v_add_f32_e32 v177, v177, v81
	v_add_f32_e32 v174, v174, v82
	v_add_f32_e32 v175, v175, v83
	v_add_f32_e32 v176, v176, v84
	s_waitcnt lgkmcnt(2)
	v_mfma_f32_32x32x16_bf16 v[98:113], v[154:157], v[138:141], v[98:113]
	v_add_f32_e32 v177, v177, v85
	v_add_f32_e32 v174, v174, v86
	v_add_f32_e32 v175, v175, v87
	v_add_f32_e32 v176, v176, v88
	v_add_f32_e32 v177, v177, v89
	s_waitcnt lgkmcnt(1)
	v_mfma_f32_32x32x16_bf16 v[114:129], v[150:153], v[142:145], v[114:129]
	v_add_f32_e32 v174, v174, v90
	v_add_f32_e32 v175, v175, v91
	v_add_f32_e32 v176, v176, v92
	v_add_f32_e32 v177, v177, v93
	s_waitcnt lgkmcnt(0)
	v_mfma_f32_32x32x16_bf16 v[98:113], v[146:149], v[142:145], v[98:113]
	v_add_f32_e32 v174, v174, v94
	v_add_f32_e32 v175, v175, v95
	v_add_f32_e32 v176, v176, v96
	v_add_f32_e32 v177, v177, v97
	v_add_f32_e32 v174, v174, v175
	v_add_f32_e32 v176, v176, v177
	v_cvt_pk_bf16_f32 v66, v66, v67
	v_cvt_pk_bf16_f32 v67, v68, v69
	v_cvt_pk_bf16_f32 v68, v70, v71
	v_cvt_pk_bf16_f32 v69, v72, v73
	v_add_f32_e32 v174, v174, v176
	v_cvt_pk_bf16_f32 v70, v74, v75
	v_cvt_pk_bf16_f32 v71, v76, v77
	v_cvt_pk_bf16_f32 v72, v78, v79
	v_cvt_pk_bf16_f32 v73, v80, v81
	v_cvt_pk_bf16_f32 v74, v82, v83
	v_cvt_pk_bf16_f32 v75, v84, v85
	v_cvt_pk_bf16_f32 v76, v86, v87
	v_cvt_pk_bf16_f32 v77, v88, v89
	v_cvt_pk_bf16_f32 v78, v90, v91
	v_cvt_pk_bf16_f32 v79, v92, v93
	v_cvt_pk_bf16_f32 v80, v94, v95
	v_cvt_pk_bf16_f32 v81, v96, v97
	v_add_f32_e32 v0, v174, v213
	ds_read_b128 v[82:85], v208 offset:32768
	ds_read_b128 v[86:89], v208 offset:36864
	ds_read_b128 v[90:93], v208 offset:40960
	ds_read_b128 v[94:97], v208 offset:45056
	ds_read_b128 v[146:149], v209 offset:32768
	ds_read_b128 v[150:153], v209 offset:36864
	ds_read_b128 v[154:157], v209 offset:40960
	ds_read_b128 v[158:161], v209 offset:45056
	s_add_i32 s14, s77, 0xffff0000
	s_and_b32 s14, s14, 0x3e0000
	s_lshl_b32 s22, s14, 1
	s_mov_b32 m0, s70
	s_add_u32 s100, s46, s22
	s_addc_u32 s101, s47, 0
	global_load_lds_dwordx4 v188, s[100:101]
	s_nop 0
	s_mov_b32 m0, s29
	s_lshl_b32 s22, s80, 1
	global_load_lds_dwordx4 v192, s[100:101]
	s_add_u32 s100, s50, s22
	s_addc_u32 s101, s51, 0
	s_add_i32 m0, s70, 0xc000
	s_nop 0
	global_load_lds_dwordx4 v190, s[100:101]
	s_nop 0
	s_add_i32 m0, s70, 0xc400
	s_nop 0
	global_load_lds_dwordx4 v194, s[100:101]
	s_waitcnt lgkmcnt(0)
	v_mfma_f32_32x32x16_bf16 v[50:65], v[66:69], v[82:85], v[50:65]
	ds_read_b128 v[82:85], v210 offset:32768
	v_exp_f32_e32 v114, v114
	v_exp_f32_e32 v115, v115
	v_mfma_f32_32x32x16_bf16 v[34:49], v[66:69], v[86:89], v[34:49]
	ds_read_b128 v[86:89], v210 offset:36864
	v_exp_f32_e32 v116, v116
	v_exp_f32_e32 v117, v117
	v_mfma_f32_32x32x16_bf16 v[18:33], v[66:69], v[90:93], v[18:33]
	ds_read_b128 v[90:93], v210 offset:40960
	v_exp_f32_e32 v118, v118
	v_exp_f32_e32 v119, v119
	v_mfma_f32_32x32x16_bf16 v[2:17], v[66:69], v[94:97], v[2:17]
	ds_read_b128 v[66:69], v210 offset:45056
	v_exp_f32_e32 v120, v120
	v_exp_f32_e32 v121, v121
	v_mfma_f32_32x32x16_bf16 v[50:65], v[70:73], v[146:149], v[50:65]
	ds_read_b128 v[94:97], v212 offset:32768
	v_exp_f32_e32 v122, v122
	v_exp_f32_e32 v123, v123
	v_mfma_f32_32x32x16_bf16 v[34:49], v[70:73], v[150:153], v[34:49]
	ds_read_b128 v[146:149], v212 offset:36864
	v_exp_f32_e32 v124, v124
	v_exp_f32_e32 v125, v125
	v_mfma_f32_32x32x16_bf16 v[18:33], v[70:73], v[154:157], v[18:33]
	ds_read_b128 v[150:153], v212 offset:40960
	v_exp_f32_e32 v126, v126
	v_exp_f32_e32 v127, v127
	v_mfma_f32_32x32x16_bf16 v[2:17], v[70:73], v[158:161], v[2:17]
	ds_read_b128 v[70:73], v212 offset:45056
	v_exp_f32_e32 v128, v128
	v_exp_f32_e32 v129, v129
	s_waitcnt lgkmcnt(0)
	v_mfma_f32_32x32x16_bf16 v[50:65], v[74:77], v[82:85], v[50:65]
	v_exp_f32_e32 v98, v98
	v_exp_f32_e32 v99, v99
	v_mfma_f32_32x32x16_bf16 v[34:49], v[74:77], v[86:89], v[34:49]
	v_exp_f32_e32 v100, v100
	v_exp_f32_e32 v101, v101
	v_mfma_f32_32x32x16_bf16 v[18:33], v[74:77], v[90:93], v[18:33]
	v_exp_f32_e32 v102, v102
	v_exp_f32_e32 v103, v103
	v_mfma_f32_32x32x16_bf16 v[2:17], v[74:77], v[66:69], v[2:17]
	v_exp_f32_e32 v104, v104
	v_exp_f32_e32 v105, v105
	v_mfma_f32_32x32x16_bf16 v[50:65], v[78:81], v[94:97], v[50:65]
	v_exp_f32_e32 v106, v106
	v_exp_f32_e32 v107, v107
	v_mfma_f32_32x32x16_bf16 v[34:49], v[78:81], v[146:149], v[34:49]
	v_exp_f32_e32 v108, v108
	v_exp_f32_e32 v109, v109
	v_mfma_f32_32x32x16_bf16 v[18:33], v[78:81], v[150:153], v[18:33]
	v_exp_f32_e32 v110, v110
	v_exp_f32_e32 v111, v111
	v_mfma_f32_32x32x16_bf16 v[2:17], v[78:81], v[70:73], v[2:17]
	v_exp_f32_e32 v112, v112
	v_exp_f32_e32 v113, v113
	s_and_b64 s[0:1], s[0:1], exec
	s_waitcnt vmcnt(0)
	s_cselect_b32 s14, 1, 2
	s_and_b64 s[0:1], s[40:41], exec
	s_cselect_b32 s14, s14, 0
	s_cmp_eq_u32 s14, s79
	s_waitcnt vmcnt(0)
	s_barrier
	s_cbranch_scc1 .LBB0_290
	s_cmp_eq_u32 s79, 0
	s_cselect_b64 vcc, -1, 0
	s_cmp_eq_u32 s79, 2
	s_cselect_b64 s[0:1], -1, 0
	v_cndmask_b32_e64 v66, 0, v201, s[0:1]
	s_cmp_eq_u32 s14, 2
	v_cndmask_b32_e32 v66, v66, v200, vcc
	s_cselect_b64 vcc, -1, 0
	v_cndmask_b32_e32 v67, 0, v201, vcc
	v_cndmask_b32_e64 v67, v200, v67, s[40:41]
	v_sub_f32_e32 v66, v66, v67
	v_exp_f32_e32 v66, v66
	s_nop 0
	v_pk_mul_f32 v[64:65], v[66:67], v[64:65] op_sel_hi:[0,1]
	v_pk_mul_f32 v[62:63], v[66:67], v[62:63] op_sel_hi:[0,1]
	v_pk_mul_f32 v[60:61], v[66:67], v[60:61] op_sel_hi:[0,1]
	v_pk_mul_f32 v[58:59], v[66:67], v[58:59] op_sel_hi:[0,1]
	v_pk_mul_f32 v[56:57], v[66:67], v[56:57] op_sel_hi:[0,1]
	v_pk_mul_f32 v[54:55], v[66:67], v[54:55] op_sel_hi:[0,1]
	v_pk_mul_f32 v[52:53], v[66:67], v[52:53] op_sel_hi:[0,1]
	v_pk_mul_f32 v[50:51], v[66:67], v[50:51] op_sel_hi:[0,1]
	v_pk_mul_f32 v[48:49], v[66:67], v[48:49] op_sel_hi:[0,1]
	v_pk_mul_f32 v[46:47], v[66:67], v[46:47] op_sel_hi:[0,1]
	v_pk_mul_f32 v[44:45], v[66:67], v[44:45] op_sel_hi:[0,1]
	v_pk_mul_f32 v[42:43], v[66:67], v[42:43] op_sel_hi:[0,1]
	v_pk_mul_f32 v[40:41], v[66:67], v[40:41] op_sel_hi:[0,1]
	v_pk_mul_f32 v[38:39], v[66:67], v[38:39] op_sel_hi:[0,1]
	v_pk_mul_f32 v[36:37], v[66:67], v[36:37] op_sel_hi:[0,1]
	v_pk_mul_f32 v[34:35], v[66:67], v[34:35] op_sel_hi:[0,1]
	v_pk_mul_f32 v[32:33], v[66:67], v[32:33] op_sel_hi:[0,1]
	v_pk_mul_f32 v[30:31], v[66:67], v[30:31] op_sel_hi:[0,1]
	v_pk_mul_f32 v[28:29], v[66:67], v[28:29] op_sel_hi:[0,1]
	v_pk_mul_f32 v[26:27], v[66:67], v[26:27] op_sel_hi:[0,1]
	v_pk_mul_f32 v[24:25], v[66:67], v[24:25] op_sel_hi:[0,1]
	v_pk_mul_f32 v[22:23], v[66:67], v[22:23] op_sel_hi:[0,1]
	v_pk_mul_f32 v[20:21], v[66:67], v[20:21] op_sel_hi:[0,1]
	v_pk_mul_f32 v[18:19], v[66:67], v[18:19] op_sel_hi:[0,1]
	v_pk_mul_f32 v[16:17], v[66:67], v[16:17] op_sel_hi:[0,1]
	v_pk_mul_f32 v[14:15], v[66:67], v[14:15] op_sel_hi:[0,1]
	v_pk_mul_f32 v[12:13], v[66:67], v[12:13] op_sel_hi:[0,1]
	v_pk_mul_f32 v[10:11], v[66:67], v[10:11] op_sel_hi:[0,1]
	v_pk_mul_f32 v[8:9], v[66:67], v[8:9] op_sel_hi:[0,1]
	v_pk_mul_f32 v[6:7], v[66:67], v[6:7] op_sel_hi:[0,1]
	v_pk_mul_f32 v[4:5], v[66:67], v[4:5] op_sel_hi:[0,1]
	v_pk_mul_f32 v[2:3], v[66:67], v[2:3] op_sel_hi:[0,1]
	v_mul_f32_e32 v0, v0, v66
	s_branch .LBB0_291
